# adds: grid-barrier followers poll the global generation word directly instead of waiting for their XCC leader to republish it
# speedup vs baseline: 1.0082x; 1.0082x over previous
; __device__ __forceinline__ unsigned xb_ld(unsigned* p)              { return __hip_atomic_load(p, __ATOMIC_RELAXED, __HIP_MEMORY_SCOPE_AGENT); }
; __device__ __forceinline__ unsigned xb_add(unsigned* p, unsigned v) { return __hip_atomic_fetch_add(p, v, __ATOMIC_RELAXED, __HIP_MEMORY_SCOPE_AGENT); }
; #define XB_SPIN(cond, bar) do { unsigned _sp = 0; while (cond) { __builtin_amdgcn_s_sleep(1); \
;     if ((++_sp & 255u) == 0u) { if (xb_ld(&(bar)[XB_TMO])) break; if (_sp > XB_SPIN_CAP) { atomicAdd(&(bar)[XB_TMO], 1u); break; } } } } while (0)
; __device__ __forceinline__ void xcd_barrier(const XcdBarrier& b) {
;     asm volatile("s_waitcnt vmcnt(0)" ::: "memory");
;     __syncthreads();
;     if (threadIdx.x == 0) {
;         unsigned* bar = b.bar;
;         __builtin_amdgcn_s_waitcnt(0);
;         unsigned nloc = b.st[0], nx = b.st[1];
;         if (nloc == 0u) { xcd_barrier_complete(bar, b.x, nloc, nx); b.st[0] = nloc; b.st[1] = nx; }
;         const unsigned old = xb_add(&bar[XB_XSUB(b.x)], 1u);
;         const unsigned gen = old / nloc;
;         if (old + 1u == (gen + 1u) * nloc) {
;             __builtin_amdgcn_fence(__ATOMIC_RELEASE, "agent");
;             asm volatile("s_waitcnt vmcnt(0)" ::: "memory");
;             const unsigned og = xb_add(&bar[XB_TOP], 1u);
;             const unsigned tg = og / nx;
;             if (og + 1u == (tg + 1u) * nx) xb_add(&bar[XB_TOPGEN], 1u);
;             else XB_SPIN(xb_ld(&bar[XB_TOPGEN]) == tg, bar);
;             __builtin_amdgcn_fence(__ATOMIC_ACQUIRE, "agent");
;             xb_add(&bar[XB_XGEN(b.x)], 1u);
;             asm volatile("s_waitcnt vmcnt(0)" ::: "memory");
;         } else {
;             XB_SPIN(xb_ld(&bar[XB_XGEN(b.x)]) == gen, bar);
;             __builtin_amdgcn_fence(__ATOMIC_ACQUIRE, "agent");
;             asm volatile("s_waitcnt vmcnt(0)" ::: "memory");
;         }
.LBB0_187:
	v_readlane_b32 s6, v253, 61
	v_readlane_b32 s7, v253, 62
	v_cvt_f32_u32_e32 v1, v3
	v_sub_u32_e32 v5, 0, v3
	v_rcp_iflag_f32_e32 v1, v1
	s_nop 1
	global_atomic_add v4, v2, v237, s[6:7] sc0
	v_mul_f32_e32 v1, 0x4f7ffffe, v1
	v_cvt_u32_f32_e32 v1, v1
	v_mul_lo_u32 v5, v5, v1
	v_mul_hi_u32 v5, v1, v5
	v_add_u32_e32 v1, v1, v5
	s_waitcnt vmcnt(0)
	v_mul_hi_u32 v1, v4, v1
	v_mul_lo_u32 v5, v1, v3
	v_sub_u32_e32 v5, v4, v5
	v_add_u32_e32 v6, 1, v1
	v_cmp_ge_u32_e32 vcc, v5, v3
	v_add_u32_e32 v4, 1, v4
	s_nop 0
	v_cndmask_b32_e32 v1, v1, v6, vcc
	v_sub_u32_e32 v6, v5, v3
	v_cndmask_b32_e32 v5, v5, v6, vcc
	v_add_u32_e32 v6, 1, v1
	v_cmp_ge_u32_e32 vcc, v5, v3
	s_nop 1
	v_cndmask_b32_e32 v1, v1, v6, vcc
	v_mul_lo_u32 v5, v3, v1
	v_add_u32_e32 v3, v5, v3
	v_cmp_ne_u32_e32 vcc, v4, v3
	s_and_saveexec_b64 s[6:7], vcc
	s_xor_b64 s[6:7], exec, s[6:7]
	s_cbranch_execz .LBB0_201
	v_readlane_b32 s10, v254, 3
	v_readlane_b32 s11, v254, 4
	s_waitcnt lgkmcnt(0)
	s_nop 3
	global_load_dword v0, v2, s[10:11] sc1
	s_waitcnt vmcnt(0)
	v_cmp_eq_u32_e32 vcc, v0, v1
	s_and_saveexec_b64 s[10:11], vcc
	s_cbranch_execz .LBB0_200
	s_mov_b32 s40, 1
	s_mov_b64 s[12:13], 0
	s_branch .LBB0_191

; __device__ __forceinline__ unsigned xb_ld(unsigned* p)              { return __hip_atomic_load(p, __ATOMIC_RELAXED, __HIP_MEMORY_SCOPE_AGENT); }
; __device__ __forceinline__ unsigned xb_add(unsigned* p, unsigned v) { return __hip_atomic_fetch_add(p, v, __ATOMIC_RELAXED, __HIP_MEMORY_SCOPE_AGENT); }
; #define XB_SPIN(cond, bar) do { unsigned _sp = 0; while (cond) { __builtin_amdgcn_s_sleep(1); \
;     if ((++_sp & 255u) == 0u) { if (xb_ld(&(bar)[XB_TMO])) break; if (_sp > XB_SPIN_CAP) { atomicAdd(&(bar)[XB_TMO], 1u); break; } } } } while (0)
; __device__ __forceinline__ void xcd_barrier(const XcdBarrier& b) {
;     ...
;             else XB_SPIN(xb_ld(&bar[XB_TOPGEN]) == tg, bar);
;             __builtin_amdgcn_fence(__ATOMIC_ACQUIRE, "agent");
;             xb_add(&bar[XB_XGEN(b.x)], 1u);
;             asm volatile("s_waitcnt vmcnt(0)" ::: "memory");
;         } else {
;             XB_SPIN(xb_ld(&bar[XB_XGEN(b.x)]) == gen, bar);
.LBB0_193:
	v_readlane_b32 s22, v254, 3
	v_readlane_b32 s23, v254, 4
	s_add_i32 s40, s40, 1
	s_mov_b64 s[34:35], -1
	s_nop 2
	global_load_dword v0, v2, s[22:23] sc1
	s_waitcnt vmcnt(0)
	v_cmp_ne_u32_e32 vcc, v0, v1
	s_orn2_b64 s[22:23], vcc, exec
	s_branch .LBB0_190

; __device__ __forceinline__ unsigned xb_ld(unsigned* p)              { return __hip_atomic_load(p, __ATOMIC_RELAXED, __HIP_MEMORY_SCOPE_AGENT); }
; __device__ __forceinline__ unsigned xb_add(unsigned* p, unsigned v) { return __hip_atomic_fetch_add(p, v, __ATOMIC_RELAXED, __HIP_MEMORY_SCOPE_AGENT); }
; #define XB_SPIN(cond, bar) do { unsigned _sp = 0; while (cond) { __builtin_amdgcn_s_sleep(1); \
;     if ((++_sp & 255u) == 0u) { if (xb_ld(&(bar)[XB_TMO])) break; if (_sp > XB_SPIN_CAP) { atomicAdd(&(bar)[XB_TMO], 1u); break; } } } } while (0)
; __device__ __forceinline__ void xcd_barrier(const XcdBarrier& b) {
;     asm volatile("s_waitcnt vmcnt(0)" ::: "memory");
;     __syncthreads();
;     if (threadIdx.x == 0) {
;         unsigned* bar = b.bar;
;         __builtin_amdgcn_s_waitcnt(0);
;         unsigned nloc = b.st[0], nx = b.st[1];
;         if (nloc == 0u) { xcd_barrier_complete(bar, b.x, nloc, nx); b.st[0] = nloc; b.st[1] = nx; }
;         const unsigned old = xb_add(&bar[XB_XSUB(b.x)], 1u);
;         const unsigned gen = old / nloc;
;         if (old + 1u == (gen + 1u) * nloc) {
;             __builtin_amdgcn_fence(__ATOMIC_RELEASE, "agent");
;             asm volatile("s_waitcnt vmcnt(0)" ::: "memory");
;             const unsigned og = xb_add(&bar[XB_TOP], 1u);
;             const unsigned tg = og / nx;
;             if (og + 1u == (tg + 1u) * nx) xb_add(&bar[XB_TOPGEN], 1u);
;             else XB_SPIN(xb_ld(&bar[XB_TOPGEN]) == tg, bar);
;             __builtin_amdgcn_fence(__ATOMIC_ACQUIRE, "agent");
;             xb_add(&bar[XB_XGEN(b.x)], 1u);
;             asm volatile("s_waitcnt vmcnt(0)" ::: "memory");
;         } else {
;             XB_SPIN(xb_ld(&bar[XB_XGEN(b.x)]) == gen, bar);
;             __builtin_amdgcn_fence(__ATOMIC_ACQUIRE, "agent");
;             asm volatile("s_waitcnt vmcnt(0)" ::: "memory");
;         }
.LBB0_575:
	v_readlane_b32 s8, v253, 61
	v_readlane_b32 s9, v253, 62
	v_cvt_f32_u32_e32 v1, v3
	v_sub_u32_e32 v5, 0, v3
	v_rcp_iflag_f32_e32 v1, v1
	s_nop 1
	global_atomic_add v4, v2, v237, s[8:9] sc0
	v_mul_f32_e32 v1, 0x4f7ffffe, v1
	v_cvt_u32_f32_e32 v1, v1
	v_mul_lo_u32 v5, v5, v1
	v_mul_hi_u32 v5, v1, v5
	v_add_u32_e32 v1, v1, v5
	s_waitcnt vmcnt(0)
	v_mul_hi_u32 v1, v4, v1
	v_mul_lo_u32 v5, v1, v3
	v_sub_u32_e32 v5, v4, v5
	v_add_u32_e32 v6, 1, v1
	v_cmp_ge_u32_e32 vcc, v5, v3
	v_add_u32_e32 v4, 1, v4
	s_nop 0
	v_cndmask_b32_e32 v1, v1, v6, vcc
	v_sub_u32_e32 v6, v5, v3
	v_cndmask_b32_e32 v5, v5, v6, vcc
	v_add_u32_e32 v6, 1, v1
	v_cmp_ge_u32_e32 vcc, v5, v3
	s_nop 1
	v_cndmask_b32_e32 v1, v1, v6, vcc
	v_mul_lo_u32 v5, v3, v1
	v_add_u32_e32 v3, v5, v3
	v_cmp_ne_u32_e32 vcc, v4, v3
	s_and_saveexec_b64 s[8:9], vcc
	s_xor_b64 s[8:9], exec, s[8:9]
	s_cbranch_execz .LBB0_589
	v_readlane_b32 s10, v254, 3
	v_readlane_b32 s11, v254, 4
	s_waitcnt lgkmcnt(0)
	s_nop 3
	global_load_dword v0, v2, s[10:11] sc1
	s_waitcnt vmcnt(0)
	v_cmp_eq_u32_e32 vcc, v0, v1
	s_and_saveexec_b64 s[10:11], vcc
	s_cbranch_execz .LBB0_588
	s_mov_b32 s40, 1
	s_mov_b64 s[12:13], 0
	s_branch .LBB0_579

; __device__ __forceinline__ unsigned xb_ld(unsigned* p)              { return __hip_atomic_load(p, __ATOMIC_RELAXED, __HIP_MEMORY_SCOPE_AGENT); }
; __device__ __forceinline__ unsigned xb_add(unsigned* p, unsigned v) { return __hip_atomic_fetch_add(p, v, __ATOMIC_RELAXED, __HIP_MEMORY_SCOPE_AGENT); }
; #define XB_SPIN(cond, bar) do { unsigned _sp = 0; while (cond) { __builtin_amdgcn_s_sleep(1); \
;     if ((++_sp & 255u) == 0u) { if (xb_ld(&(bar)[XB_TMO])) break; if (_sp > XB_SPIN_CAP) { atomicAdd(&(bar)[XB_TMO], 1u); break; } } } } while (0)
; __device__ __forceinline__ void xcd_barrier(const XcdBarrier& b) {
;     asm volatile("s_waitcnt vmcnt(0)" ::: "memory");
;     __syncthreads();
;     if (threadIdx.x == 0) {
;         unsigned* bar = b.bar;
;         __builtin_amdgcn_s_waitcnt(0);
;         unsigned nloc = b.st[0], nx = b.st[1];
;         if (nloc == 0u) { xcd_barrier_complete(bar, b.x, nloc, nx); b.st[0] = nloc; b.st[1] = nx; }
;         const unsigned old = xb_add(&bar[XB_XSUB(b.x)], 1u);
;         const unsigned gen = old / nloc;
;         if (old + 1u == (gen + 1u) * nloc) {
;             __builtin_amdgcn_fence(__ATOMIC_RELEASE, "agent");
;             asm volatile("s_waitcnt vmcnt(0)" ::: "memory");
;             const unsigned og = xb_add(&bar[XB_TOP], 1u);
;             const unsigned tg = og / nx;
;             if (og + 1u == (tg + 1u) * nx) xb_add(&bar[XB_TOPGEN], 1u);
;             else XB_SPIN(xb_ld(&bar[XB_TOPGEN]) == tg, bar);
;             __builtin_amdgcn_fence(__ATOMIC_ACQUIRE, "agent");
;             xb_add(&bar[XB_XGEN(b.x)], 1u);
;             asm volatile("s_waitcnt vmcnt(0)" ::: "memory");
;         } else {
;             XB_SPIN(xb_ld(&bar[XB_XGEN(b.x)]) == gen, bar);
;             __builtin_amdgcn_fence(__ATOMIC_ACQUIRE, "agent");
;             asm volatile("s_waitcnt vmcnt(0)" ::: "memory");
;         }
.LBB0_1405:
	v_readlane_b32 s6, v253, 61
	v_readlane_b32 s7, v253, 62
	v_cvt_f32_u32_e32 v1, v3
	v_sub_u32_e32 v5, 0, v3
	v_rcp_iflag_f32_e32 v1, v1
	s_nop 1
	global_atomic_add v4, v2, v237, s[6:7] sc0
	v_mul_f32_e32 v1, 0x4f7ffffe, v1
	v_cvt_u32_f32_e32 v1, v1
	v_mul_lo_u32 v5, v5, v1
	v_mul_hi_u32 v5, v1, v5
	v_add_u32_e32 v1, v1, v5
	s_waitcnt vmcnt(0)
	v_mul_hi_u32 v1, v4, v1
	v_mul_lo_u32 v5, v1, v3
	v_sub_u32_e32 v5, v4, v5
	v_add_u32_e32 v6, 1, v1
	v_cmp_ge_u32_e32 vcc, v5, v3
	v_add_u32_e32 v4, 1, v4
	s_nop 0
	v_cndmask_b32_e32 v1, v1, v6, vcc
	v_sub_u32_e32 v6, v5, v3
	v_cndmask_b32_e32 v5, v5, v6, vcc
	v_add_u32_e32 v6, 1, v1
	v_cmp_ge_u32_e32 vcc, v5, v3
	s_nop 1
	v_cndmask_b32_e32 v1, v1, v6, vcc
	v_mul_lo_u32 v5, v3, v1
	v_add_u32_e32 v3, v5, v3
	v_cmp_ne_u32_e32 vcc, v4, v3
	s_and_saveexec_b64 s[6:7], vcc
	s_xor_b64 s[6:7], exec, s[6:7]
	s_cbranch_execz .LBB0_1419
	v_readlane_b32 s8, v254, 3
	v_readlane_b32 s9, v254, 4
	s_waitcnt lgkmcnt(0)
	s_nop 3
	global_load_dword v0, v2, s[8:9] sc1
	s_waitcnt vmcnt(0)
	v_cmp_eq_u32_e32 vcc, v0, v1
	s_and_saveexec_b64 s[8:9], vcc
	s_cbranch_execz .LBB0_1418
	s_mov_b32 s28, 1
	s_mov_b64 s[10:11], 0
	s_branch .LBB0_1409

; __device__ __forceinline__ unsigned xb_ld(unsigned* p)              { return __hip_atomic_load(p, __ATOMIC_RELAXED, __HIP_MEMORY_SCOPE_AGENT); }
; __device__ __forceinline__ unsigned xb_add(unsigned* p, unsigned v) { return __hip_atomic_fetch_add(p, v, __ATOMIC_RELAXED, __HIP_MEMORY_SCOPE_AGENT); }
; #define XB_SPIN(cond, bar) do { unsigned _sp = 0; while (cond) { __builtin_amdgcn_s_sleep(1); \
;     if ((++_sp & 255u) == 0u) { if (xb_ld(&(bar)[XB_TMO])) break; if (_sp > XB_SPIN_CAP) { atomicAdd(&(bar)[XB_TMO], 1u); break; } } } } while (0)
; __device__ __forceinline__ void xcd_barrier(const XcdBarrier& b) {
;     ...
;             else XB_SPIN(xb_ld(&bar[XB_TOPGEN]) == tg, bar);
;             __builtin_amdgcn_fence(__ATOMIC_ACQUIRE, "agent");
;             xb_add(&bar[XB_XGEN(b.x)], 1u);
;             asm volatile("s_waitcnt vmcnt(0)" ::: "memory");
;         } else {
;             XB_SPIN(xb_ld(&bar[XB_XGEN(b.x)]) == gen, bar);
.LBB0_1411:
	v_readlane_b32 s14, v254, 3
	v_readlane_b32 s15, v254, 4
	s_add_i32 s28, s28, 1
	s_mov_b64 s[22:23], -1
	s_nop 2
	global_load_dword v0, v2, s[14:15] sc1
	s_waitcnt vmcnt(0)
	v_cmp_ne_u32_e32 vcc, v0, v1
	s_orn2_b64 s[14:15], vcc, exec
	s_branch .LBB0_1408
